# prep waves run at most 40 chunks ahead of the slowest quarter (global ring throttle 56 -> 40) to keep ring slots closer to L2; compute-dtype comment added
# baseline (speedup 1.0000x reference)
; __device__ void phase_rwkv_dist(const Params& p, LAS unsigned char* lds, int wg, int nwg) {
;     ...
;                 if (ci >= RD_NG) { unsigned sp = 0; while (!dead && __hip_atomic_load(DONE + bh * 512 + (ci - RD_NG), __ATOMIC_RELAXED, __HIP_MEMORY_SCOPE_AGENT) < 256u) { __builtin_amdgcn_s_sleep(2); if (++sp > RD_SPIN_MAX) { if (lane == 0) atomicAdd(ERR, 1u); dead = true; } } }
.Lprep_nopend:
	v_readfirstlane_b32 s81, v252
	s_cmp_ge_u32 s81, s32
	s_cselect_b64 s[92:93], -1, 0
	v_mov_b64_e32 v[60:61], v[220:221]
	v_mov_b64_e32 v[62:63], v[222:223]
	v_mov_b64_e32 v[112:113], v[224:225]
	v_mov_b64_e32 v[94:95], v[226:227]
	v_mov_b64_e32 v[64:65], v[228:229]
	v_mov_b64_e32 v[66:67], v[230:231]
	v_mov_b64_e32 v[114:115], v[232:233]
	v_mov_b64_e32 v[96:97], v[234:235]
	v_mov_b64_e32 v[118:119], v[236:237]
	v_mov_b64_e32 v[104:105], v[238:239]
	v_mov_b64_e32 v[100:101], v[240:241]
	v_mov_b64_e32 v[108:109], v[242:243]
	v_mov_b64_e32 v[120:121], v[244:245]
	v_mov_b64_e32 v[106:107], v[246:247]
	v_mov_b64_e32 v[102:103], v[248:249]
	v_mov_b64_e32 v[110:111], v[250:251]
	s_cmpk_gt_i32 s2, 0x1ff
	s_cbranch_scc1 .LBB0_656
	s_lshl_b32 s85, s2, 11
	s_add_i32 s85, s85, s18
	s_cmp_lt_i32 s2, 56
	s_cbranch_scc1 .Lprep_nopoll
	s_lshl_b32 s86, s2, 2
	s_add_u32 s86, s19, s86
	s_addc_u32 s87, s40, 0
	s_cmp_eq_u32 s91, 0
	s_cbranch_scc1 .Lpk0_a
	global_load_dword v252, v1, s[86:87] offset:-160 sc1
	s_branch .Lpk0_j
.Lpk0_a:
	s_mov_b64 s[82:83], exec
	s_mov_b64 exec, 1
	global_atomic_add v252, v1, v1, s[86:87] offset:-160 sc0
	s_mov_b64 exec, s[82:83]

; __device__ void phase_rwkv_dist(const Params& p, LAS unsigned char* lds, int wg, int nwg) {
;     ...
;                 if (ci >= RD_NG) { unsigned sp = 0; while (!dead && __hip_atomic_load(DONE + bh * 512 + (ci - RD_NG), __ATOMIC_RELAXED, __HIP_MEMORY_SCOPE_AGENT) < 256u) { __builtin_amdgcn_s_sleep(2); if (++sp > RD_SPIN_MAX) { if (lane == 0) atomicAdd(ERR, 1u); dead = true; } } }
.LBB0_660:
	s_cmp_eq_u32 s91, 0
	s_cbranch_scc1 .Lpk1_a
	global_load_dword v101, v1, s[2:3] offset:-160 sc1
	s_branch .Lpk1_j
.Lpk1_a:
	s_mov_b64 s[82:83], exec
	s_mov_b64 exec, 1
	global_atomic_add v101, v1, v1, s[2:3] offset:-160 sc0
	s_mov_b64 exec, s[82:83]
.Lpk1_j:
	s_movk_i32 s0, 0xff
	s_waitcnt vmcnt(0)
	v_readfirstlane_b32 s81, v101
	s_cmp_ge_u32 s81, s32
	s_cbranch_scc1 .LBB0_659
	s_sleep 2
	s_cmp_eq_u32 s91, 0
	s_cbranch_scc1 .Lpk2_a
	global_load_dword v101, v1, s[2:3] offset:-160 sc1
	s_branch .Lpk2_j

; __device__ void phase_rwkv_dist(const Params& p, LAS unsigned char* lds, int wg, int nwg) {
;     ...
;                 if (ci >= RD_NG) { unsigned sp = 0; while (!dead && __hip_atomic_load(DONE + bh * 512 + (ci - RD_NG), __ATOMIC_RELAXED, __HIP_MEMORY_SCOPE_AGENT) < 256u) { __builtin_amdgcn_s_sleep(2); if (++sp > RD_SPIN_MAX) { if (lane == 0) atomicAdd(ERR, 1u); dead = true; } } }
.Lpk2_j:
	s_waitcnt vmcnt(0)
	v_readfirstlane_b32 s81, v101
	s_cmp_ge_u32 s81, s32
	s_cbranch_scc1 .LBB0_659
	s_sleep 2
	s_cmp_eq_u32 s91, 0
	s_cbranch_scc1 .Lpk3_a
	global_load_dword v101, v1, s[2:3] offset:-160 sc1
	s_branch .Lpk3_j
